# grid barrier: acquire invalidate issued right after the arrival (overlaps the wait and the XCC leader's L2 writeback; CU quiescent until the barrier opens)
# speedup vs baseline: 1.0316x; 1.0084x over previous
.LBB0_203:
	s_cmp_gt_i32 s95, 2
	v_readlane_b32 s34, v245, 7
	s_cselect_b64 s[0:1], -1, 0
	v_readlane_b32 s35, v245, 8
	s_and_b64 s[4:5], s[10:11], s[0:1]
	s_mul_i32 s8, s35, s34
	s_cmp_lt_u32 s14, 64
	s_cselect_b64 s[6:7], -1, 0
	s_mul_i32 s13, s8, s96
	s_add_u32 s8, s92, 0x200
	s_addc_u32 s9, s93, 0
	s_add_u32 s20, s92, 0x1000
	s_addc_u32 s21, s93, 0
	s_add_u32 s22, s92, 0x1100
	s_addc_u32 s23, s93, 0
	s_add_u32 s16, s92, 0x1200
	s_addc_u32 s17, s93, 0
	s_add_u32 s18, s92, 0x1300
	s_addc_u32 s19, s93, 0
	v_writelane_b32 v245, s8, 13
	s_cmp_eq_u32 s33, 15
	v_cndmask_b32_e64 v0, 0, 1, s[6:7]
	v_writelane_b32 v245, s9, 14
	s_cselect_b64 s[8:9], -1, 0
	v_writelane_b32 v245, s8, 15
	s_cmp_eq_u32 s33, 14
	s_nop 0
	v_writelane_b32 v245, s9, 16
	s_cselect_b64 s[8:9], -1, 0
	v_writelane_b32 v245, s8, 17
	s_cmp_eq_u32 s33, 13
	s_nop 0
	v_writelane_b32 v245, s9, 18
	s_cselect_b64 s[8:9], -1, 0
	v_writelane_b32 v245, s8, 19
	s_cmp_eq_u32 s33, 12
	s_nop 0
	v_writelane_b32 v245, s9, 20
	s_cselect_b64 s[8:9], -1, 0
	v_writelane_b32 v245, s8, 21
	s_cmp_eq_u32 s33, 11
	s_nop 0
	v_writelane_b32 v245, s9, 22
	s_cselect_b64 s[8:9], -1, 0
	v_writelane_b32 v245, s8, 23
	s_cmp_eq_u32 s33, 10
	s_nop 0
	v_writelane_b32 v245, s9, 24
	s_cselect_b64 s[8:9], -1, 0
	v_writelane_b32 v245, s8, 25
	s_cmp_eq_u32 s33, 9
	s_nop 0
	v_writelane_b32 v245, s9, 26
	s_cselect_b64 s[8:9], -1, 0
	v_writelane_b32 v245, s8, 27
	s_cmp_eq_u32 s33, 8
	s_nop 0
	v_writelane_b32 v245, s9, 28
	s_cselect_b64 s[8:9], -1, 0
	v_writelane_b32 v245, s8, 29
	s_cmp_eq_u32 s33, 7
	s_nop 0
	v_writelane_b32 v245, s9, 30
	s_cselect_b64 s[8:9], -1, 0
	v_writelane_b32 v245, s8, 31
	s_cmp_eq_u32 s33, 6
	s_nop 0
	v_writelane_b32 v245, s9, 32
	s_cselect_b64 s[8:9], -1, 0
	v_writelane_b32 v245, s8, 33
	s_cmp_eq_u32 s33, 5
	s_nop 0
	v_writelane_b32 v245, s9, 34
	s_cselect_b64 s[8:9], -1, 0
	v_writelane_b32 v245, s8, 35
	s_cmp_eq_u32 s33, 4
	s_nop 0
	v_writelane_b32 v245, s9, 36
	s_cselect_b64 s[8:9], -1, 0
	v_writelane_b32 v245, s8, 37
	s_cmp_eq_u32 s33, 3
	s_nop 0
	v_writelane_b32 v245, s9, 38
	s_cselect_b64 s[8:9], -1, 0
	v_writelane_b32 v245, s8, 39
	s_cmp_eq_u32 s33, 2
	s_nop 0
	v_writelane_b32 v245, s9, 40
	s_cselect_b64 s[8:9], -1, 0
	v_writelane_b32 v245, s8, 41
	s_cmp_eq_u32 s33, 1
	s_nop 0
	v_writelane_b32 v245, s9, 42
	s_cselect_b64 s[8:9], -1, 0
	v_writelane_b32 v245, s8, 43
	s_cmp_eq_u32 s33, 0
	s_nop 0
	v_writelane_b32 v245, s9, 44
	s_cselect_b64 s[8:9], -1, 0
	v_writelane_b32 v245, s8, 45
	s_nop 1
	v_writelane_b32 v245, s9, 46
	s_lshl_b32 s8, s33, 8
	s_add_u32 s8, s92, s8
	s_addc_u32 s9, s93, 0
	s_add_u32 s10, s8, 0x1400
	s_addc_u32 s11, s9, 0
	v_writelane_b32 v245, s10, 47
	s_add_u32 s8, s8, 0x2400
	s_addc_u32 s9, s9, 0
	v_writelane_b32 v245, s11, 48
	v_writelane_b32 v245, s8, 49
	s_nop 1
	v_writelane_b32 v245, s9, 50
	s_add_u32 s8, s92, 0x3400
	s_addc_u32 s9, s93, 0
	v_writelane_b32 v245, s8, 51
	s_nop 1
	v_writelane_b32 v245, s9, 52
	s_add_u32 s8, s92, 0x3500
	s_addc_u32 s9, s93, 0
	v_writelane_b32 v245, s8, 53
	s_andn2_b64 vcc, exec, s[4:5]
	v_cmp_ne_u32_e64 s[4:5], 1, v0
	v_writelane_b32 v245, s9, 54
	s_nop 0
	v_writelane_b32 v245, s4, 55
	s_nop 1
	v_writelane_b32 v245, s5, 56
	v_writelane_b32 v245, s13, 57
	v_writelane_b32 v245, s16, 58
	s_nop 1
	v_writelane_b32 v245, s17, 59
	v_writelane_b32 v245, s18, 60
	s_nop 1
	v_writelane_b32 v245, s19, 61
	s_cbranch_vccnz .LBB0_259
	s_waitcnt vmcnt(0)
	v_readlane_b32 s4, v245, 55
	v_readlane_b32 s5, v245, 56
	s_and_b64 vcc, exec, s[4:5]
	s_waitcnt vmcnt(0)
	s_barrier
	s_cbranch_vccnz .LBB0_258
	v_mbcnt_hi_u32_b32 v0, -1, v192
	v_cmp_eq_u32_e32 vcc, 0, v0
	s_and_saveexec_b64 s[4:5], vcc
	s_cbranch_execz .LBB0_257
	s_waitcnt vmcnt(0) lgkmcnt(0)
	v_mov_b32_e32 v1, 1
	v_mov_b32_e32 v0, 0x23fc0
	ds_read_b32 v2, v0
	ds_read_b32 v3, v0 offset:4
	s_getreg_b32 s12, hwreg(HW_REG_XCC_ID, 0, 4)
	s_and_b32 s12, s12, 15
	s_lshl_b32 s12, s12, 8
	s_add_i32 s10, s12, 0x1400
	s_add_i32 s12, s12, 0x2400
	v_mov_b32_e32 v5, s10
	v_mov_b32_e32 v6, s12
	global_atomic_add v7, v5, v1, s[92:93] sc0
	v_readlane_b32 s6, v244, 42
	s_add_i32 s6, s6, 1
	s_nop 0
	v_writelane_b32 v244, s6, 42
	s_waitcnt lgkmcnt(0)
	v_readfirstlane_b32 s10, v2
	v_readfirstlane_b32 s11, v3
	s_mul_i32 s10, s10, s6
	s_mul_i32 s11, s11, s6
	s_waitcnt vmcnt(0)
	v_readfirstlane_b32 s12, v7
	s_add_i32 s12, s12, 1
	s_cmp_eq_u32 s12, s10
	s_cbranch_scc0 .Lxb1_winv
	buffer_inv sc1
	buffer_wbl2 sc1
	s_waitcnt vmcnt(0)
	v_mov_b32_e32 v8, 0x3400
	global_atomic_add v7, v8, v1, s[92:93] sc0
	s_waitcnt vmcnt(0)
	v_readfirstlane_b32 s12, v7
	s_add_i32 s12, s12, 1
	s_cmp_eq_u32 s12, s11
	s_cbranch_scc0 .Lxb1_wait
	v_mov_b32_e32 v8, 0x2400
	global_atomic_add v8, v1, s[92:93]
	global_atomic_add v8, v1, s[92:93] offset:256
	global_atomic_add v8, v1, s[92:93] offset:512
	global_atomic_add v8, v1, s[92:93] offset:768
	global_atomic_add v8, v1, s[92:93] offset:1024
	global_atomic_add v8, v1, s[92:93] offset:1280
	global_atomic_add v8, v1, s[92:93] offset:1536
	global_atomic_add v8, v1, s[92:93] offset:1792
	global_atomic_add v8, v1, s[92:93] offset:2048
	global_atomic_add v8, v1, s[92:93] offset:2304
	global_atomic_add v8, v1, s[92:93] offset:2560
	global_atomic_add v8, v1, s[92:93] offset:2816
	global_atomic_add v8, v1, s[92:93] offset:3072
	global_atomic_add v8, v1, s[92:93] offset:3328
	global_atomic_add v8, v1, s[92:93] offset:3584
	global_atomic_add v8, v1, s[92:93] offset:3840
	s_branch .Lxb1_done
.Lxb1_winv:
	buffer_inv sc1
.Lxb1_wait:
	s_mov_b32 s11, 0

.Lxb1_done:
	s_waitcnt vmcnt(0)
	v_mov_b32_e32 v8, 0x5000
	global_load_dword v9, v8, s[92:93] sc1
	global_load_dword v10, v8, s[92:93] offset:256 sc1
	global_load_dword v11, v8, s[92:93] offset:512 sc1
	global_load_dword v12, v8, s[92:93] offset:768 sc1
	global_load_dword v13, v8, s[92:93] offset:1024 sc1
	global_load_dword v14, v8, s[92:93] offset:1280 sc1
	global_load_dword v15, v8, s[92:93] offset:1536 sc1
	global_load_dword v16, v8, s[92:93] offset:1792 sc1
	s_waitcnt vmcnt(0)
	v_mov_b32_e32 v2, 0
	v_add_u32_e32 v3, -1, v9
	v_and_b32_e32 v3, v3, v9
	v_or_b32_e32 v2, v2, v3
	v_add_u32_e32 v3, -1, v10
	v_and_b32_e32 v3, v3, v10
	v_or_b32_e32 v2, v2, v3
	v_add_u32_e32 v3, -1, v11
	v_and_b32_e32 v3, v3, v11
	v_or_b32_e32 v2, v2, v3
	v_add_u32_e32 v3, -1, v12
	v_and_b32_e32 v3, v3, v12
	v_or_b32_e32 v2, v2, v3
	v_add_u32_e32 v3, -1, v13
	v_and_b32_e32 v3, v3, v13
	v_or_b32_e32 v2, v2, v3
	v_add_u32_e32 v3, -1, v14
	v_and_b32_e32 v3, v3, v14
	v_or_b32_e32 v2, v2, v3
	v_add_u32_e32 v3, -1, v15
	v_and_b32_e32 v3, v3, v15
	v_or_b32_e32 v2, v2, v3
	v_add_u32_e32 v3, -1, v16
	v_and_b32_e32 v3, v3, v16
	v_or_b32_e32 v2, v2, v3
	s_nop 0
	v_readfirstlane_b32 s12, v2
	v_readlane_b32 s11, v244, 41
	s_cmp_eq_u32 s12, 0
	s_cselect_b32 s12, 1, 0
	s_cmp_eq_u32 s11, 0x100
	s_cselect_b32 s12, s12, 0
	s_nop 0
	v_writelane_b32 v244, s12, 43

.LBB0_495:
	s_cmp_gt_i32 s95, 3
	s_cselect_b64 s[4:5], -1, 0
	s_and_b64 s[0:1], s[36:37], s[4:5]
	s_andn2_b64 vcc, exec, s[0:1]
	s_cbranch_vccnz .LBB0_551
	s_waitcnt vmcnt(0)
	v_readlane_b32 s0, v245, 55
	v_readlane_b32 s1, v245, 56
	s_and_b64 vcc, exec, s[0:1]
	s_waitcnt vmcnt(0)
	s_barrier
	s_cbranch_vccnz .LBB0_550
	v_mbcnt_hi_u32_b32 v0, -1, v192
	v_cmp_eq_u32_e32 vcc, 0, v0
	s_and_saveexec_b64 s[0:1], vcc
	v_readlane_b32 s13, v245, 57
	s_cbranch_execz .LBB0_549
	s_waitcnt vmcnt(0) lgkmcnt(0)
	v_mov_b32_e32 v1, 1
	v_mov_b32_e32 v0, 0x23fc0
	ds_read_b32 v2, v0
	ds_read_b32 v3, v0 offset:4
	s_getreg_b32 s12, hwreg(HW_REG_XCC_ID, 0, 4)
	s_and_b32 s12, s12, 15
	s_lshl_b32 s12, s12, 8
	s_add_i32 s10, s12, 0x1400
	s_add_i32 s12, s12, 0x2400
	v_mov_b32_e32 v5, s10
	v_mov_b32_e32 v6, s12
	global_atomic_add v7, v5, v1, s[92:93] sc0
	v_readlane_b32 s6, v244, 42
	s_add_i32 s6, s6, 1
	s_nop 0
	v_writelane_b32 v244, s6, 42
	s_waitcnt lgkmcnt(0)
	v_readfirstlane_b32 s10, v2
	v_readfirstlane_b32 s11, v3
	s_mul_i32 s10, s10, s6
	s_mul_i32 s11, s11, s6
	s_waitcnt vmcnt(0)
	v_readfirstlane_b32 s12, v7
	s_add_i32 s12, s12, 1
	s_cmp_eq_u32 s12, s10
	s_cbranch_scc0 .Lxb2_winv
	buffer_inv sc1
	buffer_wbl2 sc1
	s_waitcnt vmcnt(0)
	v_mov_b32_e32 v8, 0x3400
	global_atomic_add v7, v8, v1, s[92:93] sc0
	s_waitcnt vmcnt(0)
	v_readfirstlane_b32 s12, v7
	s_add_i32 s12, s12, 1
	s_cmp_eq_u32 s12, s11
	s_cbranch_scc0 .Lxb2_wait
	v_mov_b32_e32 v8, 0x2400
	global_atomic_add v8, v1, s[92:93]
	global_atomic_add v8, v1, s[92:93] offset:256
	global_atomic_add v8, v1, s[92:93] offset:512
	global_atomic_add v8, v1, s[92:93] offset:768
	global_atomic_add v8, v1, s[92:93] offset:1024
	global_atomic_add v8, v1, s[92:93] offset:1280
	global_atomic_add v8, v1, s[92:93] offset:1536
	global_atomic_add v8, v1, s[92:93] offset:1792
	global_atomic_add v8, v1, s[92:93] offset:2048
	global_atomic_add v8, v1, s[92:93] offset:2304
	global_atomic_add v8, v1, s[92:93] offset:2560
	global_atomic_add v8, v1, s[92:93] offset:2816
	global_atomic_add v8, v1, s[92:93] offset:3072
	global_atomic_add v8, v1, s[92:93] offset:3328
	global_atomic_add v8, v1, s[92:93] offset:3584
	global_atomic_add v8, v1, s[92:93] offset:3840
	s_branch .Lxb2_done
.Lxb2_winv:
	buffer_inv sc1
.Lxb2_wait:
	s_mov_b32 s11, 0
.Lxb2_poll:
	global_load_dword v7, v6, s[92:93] sc1
	s_waitcnt vmcnt(0)
	v_readfirstlane_b32 s12, v7
	s_cmp_ge_u32 s12, s6
	s_cbranch_scc1 .Lxb2_done
	s_add_i32 s11, s11, 1
	s_cmp_lt_u32 s11, 0x40000
	s_cbranch_scc0 .Lxb2_done
	s_sleep 1
	s_branch .Lxb2_poll
.Lxb2_done:
	s_waitcnt vmcnt(0)
.LBB0_549:
	s_or_b64 exec, exec, s[0:1]

.LBB0_574:
	s_cmp_gt_i32 s95, 4
	s_cselect_b64 s[4:5], -1, 0
	s_and_b64 s[0:1], s[0:1], s[4:5]
	s_andn2_b64 vcc, exec, s[0:1]
	v_readlane_b32 s14, v245, 57
	s_cbranch_vccnz .LBB0_630
	s_waitcnt vmcnt(0)
	v_readlane_b32 s0, v245, 55
	v_readlane_b32 s1, v245, 56
	s_and_b64 vcc, exec, s[0:1]
	s_waitcnt vmcnt(0)
	s_barrier
	s_cbranch_vccnz .LBB0_629
	v_mbcnt_hi_u32_b32 v0, -1, v192
	v_cmp_eq_u32_e32 vcc, 0, v0
	s_and_saveexec_b64 s[0:1], vcc
	s_cbranch_execz .LBB0_628
	s_waitcnt vmcnt(0) lgkmcnt(0)
	v_mov_b32_e32 v1, 1
	v_mov_b32_e32 v0, 0x23fc0
	ds_read_b32 v2, v0
	ds_read_b32 v3, v0 offset:4
	s_getreg_b32 s12, hwreg(HW_REG_XCC_ID, 0, 4)
	s_and_b32 s12, s12, 15
	s_lshl_b32 s12, s12, 8
	s_add_i32 s10, s12, 0x1400
	s_add_i32 s12, s12, 0x2400
	v_mov_b32_e32 v5, s10
	v_mov_b32_e32 v6, s12
	global_atomic_add v7, v5, v1, s[92:93] sc0
	v_readlane_b32 s6, v244, 42
	s_add_i32 s6, s6, 1
	s_nop 0
	v_writelane_b32 v244, s6, 42
	s_waitcnt lgkmcnt(0)
	v_readfirstlane_b32 s10, v2
	v_readfirstlane_b32 s11, v3
	s_mul_i32 s10, s10, s6
	s_mul_i32 s11, s11, s6
	s_waitcnt vmcnt(0)
	v_readfirstlane_b32 s12, v7
	s_add_i32 s12, s12, 1
	s_cmp_eq_u32 s12, s10
	s_cbranch_scc0 .Lxb3_winv
	buffer_inv sc1
	buffer_wbl2 sc1
	s_waitcnt vmcnt(0)
	v_mov_b32_e32 v8, 0x3400
	global_atomic_add v7, v8, v1, s[92:93] sc0
	s_waitcnt vmcnt(0)
	v_readfirstlane_b32 s12, v7
	s_add_i32 s12, s12, 1
	s_cmp_eq_u32 s12, s11
	s_cbranch_scc0 .Lxb3_wait
	v_mov_b32_e32 v8, 0x2400
	global_atomic_add v8, v1, s[92:93]
	global_atomic_add v8, v1, s[92:93] offset:256
	global_atomic_add v8, v1, s[92:93] offset:512
	global_atomic_add v8, v1, s[92:93] offset:768
	global_atomic_add v8, v1, s[92:93] offset:1024
	global_atomic_add v8, v1, s[92:93] offset:1280
	global_atomic_add v8, v1, s[92:93] offset:1536
	global_atomic_add v8, v1, s[92:93] offset:1792
	global_atomic_add v8, v1, s[92:93] offset:2048
	global_atomic_add v8, v1, s[92:93] offset:2304
	global_atomic_add v8, v1, s[92:93] offset:2560
	global_atomic_add v8, v1, s[92:93] offset:2816
	global_atomic_add v8, v1, s[92:93] offset:3072
	global_atomic_add v8, v1, s[92:93] offset:3328
	global_atomic_add v8, v1, s[92:93] offset:3584
	global_atomic_add v8, v1, s[92:93] offset:3840
	s_branch .Lxb3_done
.Lxb3_winv:
	buffer_inv sc1
.Lxb3_wait:
	s_mov_b32 s11, 0
.Lxb3_poll:
	global_load_dword v7, v6, s[92:93] sc1
	s_waitcnt vmcnt(0)
	v_readfirstlane_b32 s12, v7
	s_cmp_ge_u32 s12, s6
	s_cbranch_scc1 .Lxb3_done
	s_add_i32 s11, s11, 1
	s_cmp_lt_u32 s11, 0x40000
	s_cbranch_scc0 .Lxb3_done
	s_sleep 1
	s_branch .Lxb3_poll
.Lxb3_done:
	s_waitcnt vmcnt(0)
.LBB0_628:
	s_or_b64 exec, exec, s[0:1]

.LBB0_684:
	s_cmp_gt_i32 s95, 5
	s_cselect_b64 s[0:1], -1, 0
	s_and_b64 s[4:5], s[40:41], s[0:1]
	v_readlane_b32 s64, v245, 53
	s_andn2_b64 vcc, exec, s[4:5]
	v_readlane_b32 s65, v245, 54
	s_cbranch_vccnz .LBB0_740
	s_waitcnt vmcnt(0)
	v_readlane_b32 s4, v245, 55
	v_readlane_b32 s5, v245, 56
	s_and_b64 vcc, exec, s[4:5]
	s_waitcnt vmcnt(0)
	s_barrier
	s_cbranch_vccnz .LBB0_739
	v_mbcnt_hi_u32_b32 v0, -1, v192
	v_cmp_eq_u32_e32 vcc, 0, v0
	s_and_saveexec_b64 s[4:5], vcc
	s_cbranch_execz .LBB0_738
	s_waitcnt vmcnt(0) lgkmcnt(0)
	v_mov_b32_e32 v1, 1
	v_readlane_b32 s11, v244, 43
	s_cmp_eq_u32 s11, 1
	s_cbranch_scc0 .Lxb4_glob
	s_and_b32 s12, s2, 7
	s_lshl_b32 s10, s12, 8
	s_add_i32 s10, s10, 0x6000
	v_mov_b32_e32 v6, s10
	global_atomic_add v6, v1, s[92:93]
	buffer_inv sc1
	v_readlane_b32 s11, v244, 41
	s_sub_i32 s11, s11, s12
	s_add_i32 s11, s11, 7
	s_lshr_b32 s11, s11, 3
	s_mul_i32 s6, s11, 1
	s_branch .Lxb4_wait
.Lxb4_glob:
	v_mov_b32_e32 v0, 0x23fc0
	ds_read_b32 v2, v0
	ds_read_b32 v3, v0 offset:4
	s_getreg_b32 s12, hwreg(HW_REG_XCC_ID, 0, 4)
	s_and_b32 s12, s12, 15
	s_lshl_b32 s12, s12, 8
	s_add_i32 s10, s12, 0x1400
	s_add_i32 s12, s12, 0x2400
	v_mov_b32_e32 v5, s10
	v_mov_b32_e32 v6, s12
	global_atomic_add v7, v5, v1, s[92:93] sc0
	v_readlane_b32 s6, v244, 42
	s_add_i32 s6, s6, 1
	s_nop 0
	v_writelane_b32 v244, s6, 42
	s_waitcnt lgkmcnt(0)
	v_readfirstlane_b32 s10, v2
	v_readfirstlane_b32 s11, v3
	s_mul_i32 s10, s10, s6
	s_mul_i32 s11, s11, s6
	s_waitcnt vmcnt(0)
	v_readfirstlane_b32 s12, v7
	s_add_i32 s12, s12, 1
	s_cmp_eq_u32 s12, s10
	s_cbranch_scc0 .Lxb4_winv
	buffer_inv sc1
	buffer_wbl2 sc1
	s_waitcnt vmcnt(0)
	v_mov_b32_e32 v8, 0x3400
	global_atomic_add v7, v8, v1, s[92:93] sc0
	s_waitcnt vmcnt(0)
	v_readfirstlane_b32 s12, v7
	s_add_i32 s12, s12, 1
	s_cmp_eq_u32 s12, s11
	s_cbranch_scc0 .Lxb4_wait
	v_mov_b32_e32 v8, 0x2400
	global_atomic_add v8, v1, s[92:93]
	global_atomic_add v8, v1, s[92:93] offset:256
	global_atomic_add v8, v1, s[92:93] offset:512
	global_atomic_add v8, v1, s[92:93] offset:768
	global_atomic_add v8, v1, s[92:93] offset:1024
	global_atomic_add v8, v1, s[92:93] offset:1280
	global_atomic_add v8, v1, s[92:93] offset:1536
	global_atomic_add v8, v1, s[92:93] offset:1792
	global_atomic_add v8, v1, s[92:93] offset:2048
	global_atomic_add v8, v1, s[92:93] offset:2304
	global_atomic_add v8, v1, s[92:93] offset:2560
	global_atomic_add v8, v1, s[92:93] offset:2816
	global_atomic_add v8, v1, s[92:93] offset:3072
	global_atomic_add v8, v1, s[92:93] offset:3328
	global_atomic_add v8, v1, s[92:93] offset:3584
	global_atomic_add v8, v1, s[92:93] offset:3840
	s_branch .Lxb4_done
.Lxb4_winv:
	buffer_inv sc1
.Lxb4_wait:
	s_mov_b32 s11, 0
.Lxb4_poll:
	global_load_dword v7, v6, s[92:93] sc1
	s_waitcnt vmcnt(0)
	v_readfirstlane_b32 s12, v7
	s_cmp_ge_u32 s12, s6
	s_cbranch_scc1 .Lxb4_done
	s_add_i32 s11, s11, 1
	s_cmp_lt_u32 s11, 0x40000
	s_cbranch_scc0 .Lxb4_done
	s_sleep 1
	s_branch .Lxb4_poll
.Lxb4_done:
	s_waitcnt vmcnt(0)
.LBB0_738:
	s_or_b64 exec, exec, s[4:5]

.LBB0_813:
	s_cmp_gt_i32 s95, 6
	v_readlane_b32 s0, v244, 13
	s_cselect_b64 s[4:5], -1, 0
	v_readlane_b32 s1, v244, 14
	s_and_b64 s[0:1], s[0:1], s[4:5]
	v_readlane_b32 s58, v245, 3
	v_readlane_b32 s24, v245, 58
	v_readlane_b32 s30, v245, 60
	v_readlane_b32 s60, v245, 5
	s_andn2_b64 vcc, exec, s[0:1]
	v_readlane_b32 s59, v245, 4
	v_readlane_b32 s25, v245, 59
	v_readlane_b32 s31, v245, 61
	v_readlane_b32 s61, v245, 6
	s_cbranch_vccnz .LBB0_869
	s_waitcnt vmcnt(0)
	v_readlane_b32 s0, v245, 55
	v_readlane_b32 s1, v245, 56
	s_and_b64 vcc, exec, s[0:1]
	s_waitcnt vmcnt(0)
	s_barrier
	s_cbranch_vccnz .LBB0_868
	v_mbcnt_hi_u32_b32 v0, -1, v192
	v_cmp_eq_u32_e32 vcc, 0, v0
	s_and_saveexec_b64 s[0:1], vcc
	s_cbranch_execz .LBB0_867
	s_waitcnt vmcnt(0) lgkmcnt(0)
	v_mov_b32_e32 v1, 1
	v_mov_b32_e32 v0, 0x23fc0
	ds_read_b32 v2, v0
	ds_read_b32 v3, v0 offset:4
	s_getreg_b32 s12, hwreg(HW_REG_XCC_ID, 0, 4)
	s_and_b32 s12, s12, 15
	s_lshl_b32 s12, s12, 8
	s_add_i32 s10, s12, 0x1400
	s_add_i32 s12, s12, 0x2400
	v_mov_b32_e32 v5, s10
	v_mov_b32_e32 v6, s12
	global_atomic_add v7, v5, v1, s[92:93] sc0
	v_readlane_b32 s6, v244, 42
	s_add_i32 s6, s6, 1
	s_nop 0
	v_writelane_b32 v244, s6, 42
	s_waitcnt lgkmcnt(0)
	v_readfirstlane_b32 s10, v2
	v_readfirstlane_b32 s11, v3
	s_mul_i32 s10, s10, s6
	s_mul_i32 s11, s11, s6
	s_waitcnt vmcnt(0)
	v_readfirstlane_b32 s12, v7
	s_add_i32 s12, s12, 1
	s_cmp_eq_u32 s12, s10
	s_cbranch_scc0 .Lxb5_winv
	buffer_inv sc1
	buffer_wbl2 sc1
	s_waitcnt vmcnt(0)
	v_mov_b32_e32 v8, 0x3400
	global_atomic_add v7, v8, v1, s[92:93] sc0
	s_waitcnt vmcnt(0)
	v_readfirstlane_b32 s12, v7
	s_add_i32 s12, s12, 1
	s_cmp_eq_u32 s12, s11
	s_cbranch_scc0 .Lxb5_wait
	v_mov_b32_e32 v8, 0x2400
	global_atomic_add v8, v1, s[92:93]
	global_atomic_add v8, v1, s[92:93] offset:256
	global_atomic_add v8, v1, s[92:93] offset:512
	global_atomic_add v8, v1, s[92:93] offset:768
	global_atomic_add v8, v1, s[92:93] offset:1024
	global_atomic_add v8, v1, s[92:93] offset:1280
	global_atomic_add v8, v1, s[92:93] offset:1536
	global_atomic_add v8, v1, s[92:93] offset:1792
	global_atomic_add v8, v1, s[92:93] offset:2048
	global_atomic_add v8, v1, s[92:93] offset:2304
	global_atomic_add v8, v1, s[92:93] offset:2560
	global_atomic_add v8, v1, s[92:93] offset:2816
	global_atomic_add v8, v1, s[92:93] offset:3072
	global_atomic_add v8, v1, s[92:93] offset:3328
	global_atomic_add v8, v1, s[92:93] offset:3584
	global_atomic_add v8, v1, s[92:93] offset:3840
	s_branch .Lxb5_done
.Lxb5_winv:
	buffer_inv sc1
.Lxb5_wait:
	s_mov_b32 s11, 0
.Lxb5_poll:
	global_load_dword v7, v6, s[92:93] sc1
	s_waitcnt vmcnt(0)
	v_readfirstlane_b32 s12, v7
	s_cmp_ge_u32 s12, s6
	s_cbranch_scc1 .Lxb5_done
	s_add_i32 s11, s11, 1
	s_cmp_lt_u32 s11, 0x40000
	s_cbranch_scc0 .Lxb5_done
	s_sleep 1
	s_branch .Lxb5_poll
.Lxb5_done:
	s_waitcnt vmcnt(0)
.LBB0_867:
	s_or_b64 exec, exec, s[0:1]

.LBB0_908:
	s_cmp_gt_i32 s95, 7
	s_cselect_b64 s[4:5], -1, 0
	s_and_b64 s[0:1], s[0:1], s[4:5]
	s_andn2_b64 vcc, exec, s[0:1]
	s_cbranch_vccnz .LBB0_964
	s_waitcnt vmcnt(0)
	v_readlane_b32 s0, v245, 55
	v_readlane_b32 s1, v245, 56
	s_and_b64 vcc, exec, s[0:1]
	s_waitcnt lgkmcnt(0)
	s_barrier
	s_cbranch_vccnz .LBB0_963
	v_mbcnt_hi_u32_b32 v0, -1, v192
	v_cmp_eq_u32_e32 vcc, 0, v0
	s_and_saveexec_b64 s[0:1], vcc
	s_cbranch_execz .LBB0_962
	s_waitcnt vmcnt(0) lgkmcnt(0)
	v_mov_b32_e32 v1, 1
	v_readlane_b32 s11, v244, 43
	s_cmp_eq_u32 s11, 1
	s_cbranch_scc0 .Lxb6_glob
	s_and_b32 s12, s2, 7
	s_lshl_b32 s10, s12, 8
	s_add_i32 s10, s10, 0x6000
	v_mov_b32_e32 v6, s10
	global_atomic_add v6, v1, s[92:93]
	buffer_inv sc1
	v_readlane_b32 s11, v244, 41
	s_sub_i32 s11, s11, s12
	s_add_i32 s11, s11, 7
	s_lshr_b32 s11, s11, 3
	s_mul_i32 s6, s11, 2
	s_branch .Lxb6_wait

.Lxb6_winv:
	buffer_inv sc1
.Lxb6_wait:
	s_mov_b32 s11, 0
.Lxb6_poll:
	global_load_dword v7, v6, s[92:93] sc1
	s_waitcnt vmcnt(0)
	v_readfirstlane_b32 s12, v7
	s_cmp_ge_u32 s12, s6
	s_cbranch_scc1 .Lxb6_done
	s_add_i32 s11, s11, 1
	s_cmp_lt_u32 s11, 0x40000
	s_cbranch_scc0 .Lxb6_done
	s_sleep 1
	s_branch .Lxb6_poll
.Lxb6_done:
	s_waitcnt vmcnt(0)
.LBB0_962:
	s_or_b64 exec, exec, s[0:1]

.LBB0_981:
	s_cmp_gt_i32 s95, 8
	s_cselect_b64 s[4:5], -1, 0
	s_and_b64 s[0:1], s[0:1], s[4:5]
	s_andn2_b64 vcc, exec, s[0:1]
	s_cbranch_vccnz .LBB0_1037
	s_waitcnt vmcnt(0)
	v_readlane_b32 s0, v245, 55
	v_readlane_b32 s1, v245, 56
	s_and_b64 vcc, exec, s[0:1]
	s_waitcnt lgkmcnt(0)
	s_barrier
	s_cbranch_vccnz .LBB0_1036
	v_mbcnt_hi_u32_b32 v0, -1, v192
	v_cmp_eq_u32_e32 vcc, 0, v0
	s_and_saveexec_b64 s[0:1], vcc
	s_cbranch_execz .LBB0_1035
	s_waitcnt vmcnt(0) lgkmcnt(0)
	v_mov_b32_e32 v1, 1
	v_readlane_b32 s11, v244, 43
	s_cmp_eq_u32 s11, 1
	s_cbranch_scc0 .Lxb7_glob
	s_and_b32 s12, s2, 7
	s_lshl_b32 s10, s12, 8
	s_add_i32 s10, s10, 0x6000
	v_mov_b32_e32 v6, s10
	global_atomic_add v6, v1, s[92:93]
	buffer_inv sc1
	v_readlane_b32 s11, v244, 41
	s_sub_i32 s11, s11, s12
	s_add_i32 s11, s11, 7
	s_lshr_b32 s11, s11, 3
	s_mul_i32 s6, s11, 3
	s_branch .Lxb7_wait

.Lxb7_winv:
	buffer_inv sc1
.Lxb7_wait:
	s_mov_b32 s11, 0
.Lxb7_poll:
	global_load_dword v7, v6, s[92:93] sc1
	s_waitcnt vmcnt(0)
	v_readfirstlane_b32 s12, v7
	s_cmp_ge_u32 s12, s6
	s_cbranch_scc1 .Lxb7_done
	s_add_i32 s11, s11, 1
	s_cmp_lt_u32 s11, 0x40000
	s_cbranch_scc0 .Lxb7_done
	s_sleep 1
	s_branch .Lxb7_poll
.Lxb7_done:
	s_waitcnt vmcnt(0)
.LBB0_1035:
	s_or_b64 exec, exec, s[0:1]
